# in-proj panel order: c_fl panel processed first by its class
# baseline (speedup 1.0000x reference)
.LBB0_249:
	v_writelane_b32 v253, s80, 2
	s_nop 1
	v_writelane_b32 v253, s81, 3
	v_writelane_b32 v253, s76, 4
	s_nop 1
	v_writelane_b32 v253, s77, 5
	s_or_b64 exec, exec, s[4:5]
	s_cmpk_lt_i32 s90, 0x400
	s_cselect_b64 s[4:5], -1, 0
	v_writelane_b32 v253, s4, 6
	s_ashr_i32 s66, s90, 31
	s_ashr_i32 s92, s60, 31
	v_writelane_b32 v253, s5, 7
	s_lshr_b32 s4, s66, 29
	s_add_i32 s4, s90, s4
	s_ashr_i32 s9, s4, 3
	s_and_b32 s4, s4, -8
	s_sub_i32 s10, s90, s4
	s_lshl_b32 s11, s10, 7
	s_cmp_eq_u32 s3, 15
	s_cselect_b64 s[4:5], -1, 0
	v_writelane_b32 v253, s4, 8
	s_cmp_eq_u32 s3, 14
	s_mul_i32 s8, s61, s60
	v_writelane_b32 v253, s5, 9
	s_cselect_b64 s[4:5], -1, 0
	v_writelane_b32 v253, s4, 10
	s_cmp_eq_u32 s3, 13
	s_mul_i32 s12, s10, 0x81
	v_writelane_b32 v253, s5, 11
	s_cselect_b64 s[4:5], -1, 0
	v_writelane_b32 v253, s4, 12
	s_cmp_eq_u32 s3, 12
	s_mul_i32 s96, s8, s2
	v_writelane_b32 v253, s5, 13
	s_cselect_b64 s[4:5], -1, 0
	v_writelane_b32 v253, s4, 14
	s_cmp_eq_u32 s3, 11
	v_lshlrev_b64 v[0:1], 2, v[0:1]
	v_writelane_b32 v253, s5, 15
	s_cselect_b64 s[4:5], -1, 0
	v_writelane_b32 v253, s4, 16
	s_cmp_eq_u32 s3, 10
	v_mov_b32_e32 v191, 0
	v_writelane_b32 v253, s5, 17
	s_cselect_b64 s[4:5], -1, 0
	v_writelane_b32 v253, s4, 18
	s_cmp_eq_u32 s3, 9
	s_mov_b32 s81, 0
	v_writelane_b32 v253, s5, 19
	s_cselect_b64 s[4:5], -1, 0
	v_writelane_b32 v253, s4, 20
	s_cmp_eq_u32 s3, 8
	s_movk_i32 s33, 0x200
	v_writelane_b32 v253, s5, 21
	s_cselect_b64 s[4:5], -1, 0
	v_writelane_b32 v253, s4, 22
	s_cmp_eq_u32 s3, 7
	s_movk_i32 s65, 0x2000
	v_writelane_b32 v253, s5, 23
	s_cselect_b64 s[4:5], -1, 0
	v_writelane_b32 v253, s4, 24
	s_cmp_eq_u32 s3, 6
	s_movk_i32 s82, 0x6000
	v_writelane_b32 v253, s5, 25
	s_cselect_b64 s[4:5], -1, 0
	v_writelane_b32 v253, s4, 26
	s_cmp_eq_u32 s3, 5
	v_mov_b32_e32 v192, 0x358637bd
	v_writelane_b32 v253, s5, 27
	s_cselect_b64 s[4:5], -1, 0
	v_writelane_b32 v253, s4, 28
	s_cmp_eq_u32 s3, 4
	v_mov_b32_e32 v185, 0x3ecc95a3
	v_writelane_b32 v253, s5, 29
	s_cselect_b64 s[4:5], -1, 0
	v_writelane_b32 v253, s4, 30
	s_cmp_eq_u32 s3, 3
	v_mov_b32_e32 v193, 1
	v_writelane_b32 v253, s5, 31
	s_cselect_b64 s[4:5], -1, 0
	v_writelane_b32 v253, s4, 32
	s_cmp_eq_u32 s3, 2
	v_mov_b64_e32 v[194:195], 0x400
	v_writelane_b32 v253, s5, 33
	s_cselect_b64 s[4:5], -1, 0
	v_writelane_b32 v253, s4, 34
	s_cmp_eq_u32 s3, 1
	v_mov_b64_e32 v[196:197], 0x3ff
	v_writelane_b32 v253, s5, 35
	s_cselect_b64 s[4:5], -1, 0
	v_writelane_b32 v253, s4, 36
	s_cmp_eq_u32 s3, 0
	v_mov_b32_e32 v224, 0x3e38aa3b
	v_writelane_b32 v253, s5, 37
	s_cselect_b64 s[4:5], -1, 0
	v_writelane_b32 v253, s4, 38
	s_cmpk_lt_i32 s78, 0x200
	v_mov_b32_e32 v225, 0x41b17218
	v_writelane_b32 v253, s5, 39
	s_cselect_b64 s[4:5], -1, 0
	s_lshl_b32 s72, s60, 1
	v_writelane_b32 v253, s4, 40
	s_cmpk_lt_i32 s78, 0x100
	v_mov_b32_e32 v226, 0x7f800000
	v_writelane_b32 v253, s5, 41
	s_cselect_b64 s[4:5], -1, 0
	v_writelane_b32 v253, s4, 42
	s_cmp_lt_i32 s78, 32
	v_mbcnt_hi_u32_b32 v227, -1, v78
	v_writelane_b32 v253, s5, 43
	s_cselect_b64 s[4:5], -1, 0
	v_writelane_b32 v253, s4, 44
	s_cmpk_eq_i32 s60, 0x100
	v_mov_b32_e32 v228, 0xff800000
	v_writelane_b32 v253, s5, 45
	s_cselect_b64 s[4:5], -1, 0
	v_writelane_b32 v253, s4, 46
	s_cmpk_lg_i32 s60, 0x100
	v_mov_b32_e32 v236, v191
	v_writelane_b32 v253, s5, 47
	s_cselect_b64 s[4:5], -1, 0
	v_writelane_b32 v253, s4, 48
	s_cmpk_lt_i32 s90, 0x100
	v_mov_b32_e32 v237, v191
	v_writelane_b32 v253, s5, 49
	s_cselect_b64 s[4:5], -1, 0
	v_writelane_b32 v253, s4, 50
	s_lshl_b32 s3, s10, 5
	v_mov_b64_e32 v[198:199], 0x100
	v_writelane_b32 v253, s5, 51
	s_getpc_b64 s[4:5]
	s_add_u32 s4, s4, g_ctl@rel32@lo+9220
	s_addc_u32 s5, s5, g_ctl@rel32@hi+9228
	s_getpc_b64 s[6:7]
	s_add_u32 s6, s6, g_ctl@rel32@lo+5124
	s_addc_u32 s7, s7, g_ctl@rel32@hi+5132
	s_cmp_lt_i32 s10, 0
	s_mul_i32 s10, s10, 33
	s_cselect_b32 s2, s12, s11
	s_cselect_b32 s3, s10, s3
	s_add_i32 s2, s2, s9
	v_lshl_add_u64 v[188:189], s[4:5], 0, v[0:1]
	s_ashr_i32 s4, s2, 31
	s_lshr_b32 s4, s4, 25
	s_add_i32 s4, s2, s4
	s_ashr_i32 s5, s4, 7
	s_and_b32 s4, s4, 0xff80
	s_sub_i32 s4, s2, s4
	s_bfe_i32 s2, s4, 0x80000
	s_bfe_u32 s2, s2, 0x3000c
	v_lshl_add_u64 v[186:187], s[6:7], 0, v[0:1]
	s_add_i32 s6, s4, s2
	s_bfe_i32 s2, s6, 0x80000
	s_and_b32 s6, s6, 0xf8
	s_sub_i32 s4, s4, s6
	s_lshl_b32 s5, s5, 3
	s_sext_i32_i16 s7, s2
	s_sext_i32_i8 s4, s4
	s_add_i32 s8, s5, s4
	s_ashr_i32 s4, s7, 3
	s_mov_b32 s100, 0x7654f21b
	s_mov_b32 s101, 0x3edc9a08
	s_lshl_b32 s4, s4, 2
	s_lshr_b64 s[100:101], s[100:101], s4
	s_and_b32 s4, s100, 15
	s_add_i32 s3, s3, s9
	v_writelane_b32 v253, s4, 52
	s_ashr_i32 s4, s3, 31
	s_lshr_b32 s4, s4, 27
	s_add_i32 s4, s3, s4
	s_ashr_i32 s5, s4, 5
	s_and_b32 s4, s4, 0xffe0
	s_sub_i32 s3, s3, s4
	s_bfe_i32 s4, s3, 0x80000
	s_bfe_u32 s4, s4, 0x3000c
	s_add_i32 s6, s3, s4
	s_bfe_i32 s4, s6, 0x80000
	s_and_b32 s6, s6, 0xf8
	s_sub_i32 s3, s3, s6
	s_lshr_b32 s2, s7, 3
	s_mov_b32 s100, 0x7654f21b
	s_mov_b32 s101, 0x3edc9a08
	s_lshl_b32 s2, s2, 2
	s_lshr_b64 s[100:101], s[100:101], s2
	s_and_b32 s2, s100, 15
	s_lshl_b32 s5, s5, 3
	s_sext_i32_i16 s7, s4
	s_sext_i32_i8 s3, s3
	s_add_i32 s10, s5, s3
	s_ashr_i32 s3, s7, 3
	v_writelane_b32 v253, s3, 53
	s_mov_b32 s6, s8
	s_lshr_b32 s4, s7, 3
	s_ashr_i32 s9, s8, 31
	v_writelane_b32 v253, s6, 54
	s_bfe_i64 s[2:3], s[2:3], 0x100000
	s_lshl_b64 s[2:3], s[2:3], 19
	v_writelane_b32 v253, s7, 55
	s_lshl_b64 s[6:7], s[8:9], 19
	v_writelane_b32 v253, s6, 56
	s_ashr_i32 s11, s10, 31
	s_ashr_i32 s79, s78, 31
	v_writelane_b32 v253, s7, 57
	v_writelane_b32 v253, s2, 58
	s_lshl_b32 s87, s60, 2
	v_mov_b64_e32 v[200:201], 0xff
	v_writelane_b32 v253, s3, 59
	s_mov_b32 s2, s10
	v_writelane_b32 v253, s2, 60
	s_mov_b32 s97, 0x18000
	s_mov_b32 s88, 0x1a000
	v_writelane_b32 v253, s3, 61
	s_lshl_b64 s[2:3], s[10:11], 19
	v_writelane_b32 v253, s2, 62
	s_mov_b32 s89, 0x8000
	s_mov_b32 s91, 0x1c000
	v_writelane_b32 v253, s3, 63
	s_bfe_i64 s[2:3], s[4:5], 0x100000
	s_lshl_b64 s[2:3], s[2:3], 19
	v_writelane_b32 v252, s2, 0
	s_mov_b32 s93, 0x800000
	s_mov_b32 s94, 0xbfb8aa3b
	v_writelane_b32 v252, s3, 1
	s_lshl_b32 s2, s78, 7
	v_writelane_b32 v252, s2, 2
	s_lshl_b32 s2, s60, 8
	v_writelane_b32 v252, s2, 3
	s_lshl_b32 s2, s78, 1
	v_writelane_b32 v252, s2, 4
	s_lshl_b64 s[2:3], s[78:79], 14
	s_add_u32 s2, s2, 0x1800000
	v_writelane_b32 v252, s2, 5
	s_addc_u32 s2, s3, 0
	s_ashr_i32 s73, s72, 31
	v_writelane_b32 v252, s2, 6
	s_lshl_b64 s[2:3], s[72:73], 14
	v_writelane_b32 v252, s2, 7
	s_mov_b32 s95, 0x3f317217
	s_mov_b32 s62, 0x7f800000
	v_writelane_b32 v252, s3, 8
	s_mov_b32 s2, s78
	v_writelane_b32 v252, s2, 9
	s_movk_i32 s70, 0x1e00
	s_movk_i32 s71, 0x90
	v_writelane_b32 v252, s3, 10
	s_lshl_b64 s[2:3], s[78:79], 8
	s_add_u32 s2, s2, 0x1600000
	v_writelane_b32 v252, s2, 11
	s_addc_u32 s2, s3, 0
	v_writelane_b32 v252, s2, 12
	s_add_i32 s2, 0, 0x23fc0
	v_writelane_b32 v252, s2, 13
	s_add_i32 s2, 0, 0x23fc4
	v_writelane_b32 v252, s2, 14
	s_add_i32 s2, 0, 0x4400
	v_writelane_b32 v252, s2, 15
	s_add_i32 s2, 0, 0x15c00
	v_writelane_b32 v252, s2, 16
	s_add_i32 s2, 0, 0x20800
	v_writelane_b32 v252, s2, 17
	s_lshl_b64 s[2:3], s[72:73], 8
	v_writelane_b32 v252, s2, 18
	s_movk_i32 s79, 0x4000
	s_mov_b32 s64, 0xb2a5705f
	s_mov_b32 s58, 0x42ce8ed0
	s_mov_b32 s59, 0xc2b17218
	s_mov_b32 s77, 0x3f2aaaab
	s_mov_b32 s78, 0x3f317218
	s_mov_b32 s63, 0x33800000
	s_movk_i32 s76, 0x1000
	s_mov_b32 s4, 0x9000
	s_mov_b32 s9, 0xb000
	s_mov_b32 s5, 0xf000
	s_mov_b32 s6, 0x11000
	s_mov_b32 s7, 0x13000
	s_mov_b32 s86, 0x15000
	s_mov_b32 s61, 0x17000
	v_writelane_b32 v252, s3, 19
	s_movk_i32 s73, 0x3000
	s_mov_b32 s67, 0xa000
	s_mov_b64 s[14:15], -1
	s_mov_b64 s[2:3], 0
	s_mov_b64 s[84:85], 0x80
	s_mov_b32 s8, 0x3c800000
	s_mov_b32 s16, s81
	s_barrier
	s_branch .LBB0_253

.LBB0_265:
	s_mov_b32 s2, 0x7654f21b
	s_mov_b32 s3, 0x3edc9a08
	s_lshl_b32 s22, s22, 2
	s_lshr_b64 s[2:3], s[2:3], s22
	s_and_b32 s22, s2, 15
	s_ashr_i32 s25, s24, 31
	s_lshl_b64 s[26:27], s[24:25], 19
	s_add_u32 s26, s73, s26
	s_addc_u32 s27, s74, s27
	s_and_b64 s[28:29], s[40:41], exec
	s_cselect_b32 s25, s27, s31
	s_cselect_b32 s43, s26, s30
	s_ashr_i32 s23, s22, 31
	s_lshl_b64 s[28:29], s[22:23], 19
	s_add_u32 s28, s75, s28
	s_addc_u32 s29, s12, s29
	s_and_b64 s[36:37], s[40:41], exec
	s_cselect_b32 s23, s29, s35
	s_cselect_b32 s44, s28, s34
	s_add_u32 s30, s30, 0x40080
	s_addc_u32 s31, s31, 0
	s_add_u32 s45, s34, 0x100
	v_mov_b32_e32 v64, 0
	s_addc_u32 s46, s35, 0
	s_mov_b32 s47, -2
	v_mov_b32_e32 v65, v64
	v_mov_b32_e32 v66, v64
	v_mov_b32_e32 v67, v64
	v_mov_b32_e32 v68, v64
	v_mov_b32_e32 v69, v64
	v_mov_b32_e32 v70, v64
	v_mov_b32_e32 v71, v64
	v_mov_b32_e32 v72, v64
	v_mov_b32_e32 v73, v64
	v_mov_b32_e32 v74, v64
	v_mov_b32_e32 v75, v64
	v_mov_b32_e32 v76, v64
	v_mov_b32_e32 v77, v64
	v_mov_b32_e32 v78, v64
	v_mov_b32_e32 v79, v64
	v_mov_b32_e32 v80, v64
	v_mov_b32_e32 v81, v64
	v_mov_b32_e32 v82, v64
	v_mov_b32_e32 v83, v64
	v_mov_b32_e32 v84, v64
	v_mov_b32_e32 v85, v64
	v_mov_b32_e32 v86, v64
	v_mov_b32_e32 v87, v64
	v_mov_b32_e32 v88, v64
	v_mov_b32_e32 v89, v64
	v_mov_b32_e32 v90, v64
	v_mov_b32_e32 v91, v64
	v_mov_b32_e32 v92, v64
	v_mov_b32_e32 v93, v64
	v_mov_b32_e32 v94, v64
	v_mov_b32_e32 v95, v64
	v_mov_b32_e32 v0, v64
	v_mov_b32_e32 v1, v64
	v_mov_b32_e32 v2, v64
	v_mov_b32_e32 v3, v64
	v_mov_b32_e32 v4, v64
	v_mov_b32_e32 v5, v64
	v_mov_b32_e32 v6, v64
	v_mov_b32_e32 v7, v64
	v_mov_b32_e32 v8, v64
	v_mov_b32_e32 v9, v64
	v_mov_b32_e32 v10, v64
	v_mov_b32_e32 v11, v64
	v_mov_b32_e32 v12, v64
	v_mov_b32_e32 v13, v64
	v_mov_b32_e32 v14, v64
	v_mov_b32_e32 v15, v64
	v_mov_b32_e32 v16, v64
	v_mov_b32_e32 v17, v64
	v_mov_b32_e32 v18, v64
	v_mov_b32_e32 v19, v64
	v_mov_b32_e32 v20, v64
	v_mov_b32_e32 v21, v64
	v_mov_b32_e32 v22, v64
	v_mov_b32_e32 v23, v64
	v_mov_b32_e32 v24, v64
	v_mov_b32_e32 v25, v64
	v_mov_b32_e32 v26, v64
	v_mov_b32_e32 v27, v64
	v_mov_b32_e32 v28, v64
	v_mov_b32_e32 v29, v64
	v_mov_b32_e32 v30, v64
	v_mov_b32_e32 v31, v64
	v_mov_b32_e32 v96, v64
	v_mov_b32_e32 v97, v64
	v_mov_b32_e32 v98, v64
	v_mov_b32_e32 v99, v64
	v_mov_b32_e32 v100, v64
	v_mov_b32_e32 v101, v64
	v_mov_b32_e32 v102, v64
	v_mov_b32_e32 v103, v64
	v_mov_b32_e32 v104, v64
	v_mov_b32_e32 v105, v64
	v_mov_b32_e32 v106, v64
	v_mov_b32_e32 v107, v64
	v_mov_b32_e32 v108, v64
	v_mov_b32_e32 v109, v64
	v_mov_b32_e32 v110, v64
	v_mov_b32_e32 v111, v64
	v_mov_b32_e32 v112, v64
	v_mov_b32_e32 v113, v64
	v_mov_b32_e32 v114, v64
	v_mov_b32_e32 v115, v64
	v_mov_b32_e32 v116, v64
	v_mov_b32_e32 v117, v64
	v_mov_b32_e32 v118, v64
	v_mov_b32_e32 v119, v64
	v_mov_b32_e32 v120, v64
	v_mov_b32_e32 v121, v64
	v_mov_b32_e32 v122, v64
	v_mov_b32_e32 v123, v64
	v_mov_b32_e32 v124, v64
	v_mov_b32_e32 v125, v64
	v_mov_b32_e32 v126, v64
	v_mov_b32_e32 v127, v64
	v_mov_b32_e32 v32, v64
	v_mov_b32_e32 v33, v64
	v_mov_b32_e32 v34, v64
	v_mov_b32_e32 v35, v64
	v_mov_b32_e32 v36, v64
	v_mov_b32_e32 v37, v64
	v_mov_b32_e32 v38, v64
	v_mov_b32_e32 v39, v64
	v_mov_b32_e32 v40, v64
	v_mov_b32_e32 v41, v64
	v_mov_b32_e32 v42, v64
	v_mov_b32_e32 v43, v64
	v_mov_b32_e32 v44, v64
	v_mov_b32_e32 v45, v64
	v_mov_b32_e32 v46, v64
	v_mov_b32_e32 v47, v64
	v_mov_b32_e32 v48, v64
	v_mov_b32_e32 v49, v64
	v_mov_b32_e32 v50, v64
	v_mov_b32_e32 v51, v64
	v_mov_b32_e32 v52, v64
	v_mov_b32_e32 v53, v64
	v_mov_b32_e32 v54, v64
	v_mov_b32_e32 v55, v64
	v_mov_b32_e32 v56, v64
	v_mov_b32_e32 v57, v64
	v_mov_b32_e32 v58, v64
	v_mov_b32_e32 v59, v64
	v_mov_b32_e32 v60, v64
	v_mov_b32_e32 v61, v64
	v_mov_b32_e32 v62, v64
	v_mov_b32_e32 v63, v64
